# v26 + GEMM accumulator zeroing with v_mov_b64 (64 instead of 128 moves per tile, 9 instances)
# speedup vs baseline: 1.0031x; 1.0031x over previous
; template <class Epi, class Sched>
; __device__ __forceinline__ void gemm_phase(LAS unsigned char* lds, const Gemm g, const Sched& S, const Epi& E, int wave_id) {
;     ...
;         const bool has_next = S.next(ui + 1, nxt);
;         const char* nA = has_next ? (const char*)g.A + nxt.a_off : cA; const char* nB = has_next ? (const char*)g.Bt + nxt.b_off : cB;
;         for (int t = 0; t < nt; t += 2) {
;             const bool last = (t == nt - 2);
;             const char* a1 = cA + (size_t)(t + 1) * kstep;
;             const char* a2 = last ? nA : cA + (size_t)(t + 2) * kstep; const char* b2 = last ? nB : cB + (size_t)(t + 2) * kstep;
;             const char* a3 = a2 + kstep; const char* b3 = b2 + kstep;
;     ...
;         for (int a = 0; a < 2; ++a)
; #pragma unroll
;             for (int b = 0; b < 2; ++b)
; #pragma unroll
;                 for (int m = 0; m < 4; ++m)
; #pragma unroll
;                     for (int n = 0; n < 2; ++n) acc[a][b][m][n] = (f32x4){0.f, 0.f, 0.f, 0.f};
.LBB0_171:
	s_add_u32 s26, s76, s40
	s_addc_u32 s27, s77, s41
	s_and_b64 s[6:7], s[38:39], exec
	s_cselect_b32 s18, s27, s45
	s_cselect_b32 s19, s26, s44
	s_add_u32 s30, s76, s42
	s_addc_u32 s31, s77, s43
	s_and_b64 s[6:7], s[38:39], exec
	s_cselect_b32 s21, s31, s3
	s_cselect_b32 s22, s30, s2
	s_add_u32 s24, s2, 0x100
	v_mov_b32_e32 v2, 0
	s_addc_u32 s25, s3, 0
	s_mov_b32 s58, -2
	v_mov_b64_e32 v[2:3], 0
	v_mov_b64_e32 v[4:5], 0
	v_mov_b64_e32 v[6:7], 0
	v_mov_b64_e32 v[8:9], 0
	v_mov_b64_e32 v[10:11], 0
	v_mov_b64_e32 v[12:13], 0
	v_mov_b64_e32 v[14:15], 0
	v_mov_b64_e32 v[16:17], 0
	v_mov_b64_e32 v[18:19], 0
	v_mov_b64_e32 v[20:21], 0
	v_mov_b64_e32 v[22:23], 0
	v_mov_b64_e32 v[24:25], 0
	v_mov_b64_e32 v[26:27], 0
	v_mov_b64_e32 v[28:29], 0
	v_mov_b64_e32 v[30:31], 0
	v_mov_b64_e32 v[32:33], 0
	v_mov_b64_e32 v[34:35], 0
	v_mov_b64_e32 v[36:37], 0
	v_mov_b64_e32 v[38:39], 0
	v_mov_b64_e32 v[40:41], 0
	v_mov_b64_e32 v[42:43], 0
	v_mov_b64_e32 v[44:45], 0
	v_mov_b64_e32 v[46:47], 0
	v_mov_b64_e32 v[48:49], 0
	v_mov_b64_e32 v[50:51], 0
	v_mov_b64_e32 v[52:53], 0
	v_mov_b64_e32 v[54:55], 0
	v_mov_b64_e32 v[56:57], 0
	v_mov_b64_e32 v[58:59], 0
	v_mov_b64_e32 v[60:61], 0
	v_mov_b64_e32 v[62:63], 0
	v_mov_b64_e32 v[64:65], 0
	v_mov_b64_e32 v[66:67], 0
	v_mov_b64_e32 v[68:69], 0
	v_mov_b64_e32 v[70:71], 0
	v_mov_b64_e32 v[72:73], 0
	v_mov_b64_e32 v[74:75], 0
	v_mov_b64_e32 v[76:77], 0
	v_mov_b64_e32 v[78:79], 0
	v_mov_b64_e32 v[80:81], 0
	v_mov_b64_e32 v[82:83], 0
	v_mov_b64_e32 v[84:85], 0
	v_mov_b64_e32 v[86:87], 0
	v_mov_b64_e32 v[88:89], 0
	v_mov_b64_e32 v[90:91], 0
	v_mov_b64_e32 v[92:93], 0
	v_mov_b64_e32 v[94:95], 0
	v_mov_b64_e32 v[96:97], 0
	v_mov_b64_e32 v[98:99], 0
	v_mov_b64_e32 v[100:101], 0
	v_mov_b64_e32 v[102:103], 0
	v_mov_b64_e32 v[104:105], 0
	v_mov_b64_e32 v[106:107], 0
	v_mov_b64_e32 v[108:109], 0
	v_mov_b64_e32 v[110:111], 0
	v_mov_b64_e32 v[112:113], 0
	v_mov_b64_e32 v[114:115], 0
	v_mov_b64_e32 v[116:117], 0
	v_mov_b64_e32 v[118:119], 0
	v_mov_b64_e32 v[120:121], 0
	v_mov_b64_e32 v[122:123], 0
	v_mov_b64_e32 v[124:125], 0
	v_mov_b64_e32 v[126:127], 0
	v_mov_b64_e32 v[128:129], 0

; template <class Epi, class Sched>
; __device__ __forceinline__ void gemm_phase(LAS unsigned char* lds, const Gemm g, const Sched& S, const Epi& E, int wave_id) {
;     ...
;         const bool has_next = S.next(ui + 1, nxt);
;         const char* nA = has_next ? (const char*)g.A + nxt.a_off : cA; const char* nB = has_next ? (const char*)g.Bt + nxt.b_off : cB;
;         for (int t = 0; t < nt; t += 2) {
;             const bool last = (t == nt - 2);
;             const char* a1 = cA + (size_t)(t + 1) * kstep;
;             const char* a2 = last ? nA : cA + (size_t)(t + 2) * kstep; const char* b2 = last ? nB : cB + (size_t)(t + 2) * kstep;
;             const char* a3 = a2 + kstep; const char* b3 = b2 + kstep;
;     ...
;         for (int a = 0; a < 2; ++a)
; #pragma unroll
;             for (int b = 0; b < 2; ++b)
; #pragma unroll
;                 for (int m = 0; m < 4; ++m)
; #pragma unroll
;                     for (int n = 0; n < 2; ++n) acc[a][b][m][n] = (f32x4){0.f, 0.f, 0.f, 0.f};
.LBB0_251:
	s_add_u32 s44, s72, s40
	s_addc_u32 s45, s73, s41
	s_and_b64 s[6:7], s[38:39], exec
	s_cselect_b32 s12, s45, s27
	s_cselect_b32 s13, s44, s26
	s_add_u32 s46, s62, s42
	s_addc_u32 s47, s63, s43
	s_and_b64 s[6:7], s[38:39], exec
	s_cselect_b32 s18, s47, s3
	s_cselect_b32 s19, s46, s2
	s_add_u32 s21, s2, 0x100
	v_mov_b32_e32 v2, 0
	s_addc_u32 s22, s3, 0
	s_mov_b32 s24, -2
	v_mov_b64_e32 v[2:3], 0
	v_mov_b64_e32 v[4:5], 0
	v_mov_b64_e32 v[6:7], 0
	v_mov_b64_e32 v[8:9], 0
	v_mov_b64_e32 v[10:11], 0
	v_mov_b64_e32 v[12:13], 0
	v_mov_b64_e32 v[14:15], 0
	v_mov_b64_e32 v[16:17], 0
	v_mov_b64_e32 v[18:19], 0
	v_mov_b64_e32 v[20:21], 0
	v_mov_b64_e32 v[22:23], 0
	v_mov_b64_e32 v[24:25], 0
	v_mov_b64_e32 v[26:27], 0
	v_mov_b64_e32 v[28:29], 0
	v_mov_b64_e32 v[30:31], 0
	v_mov_b64_e32 v[32:33], 0
	v_mov_b64_e32 v[34:35], 0
	v_mov_b64_e32 v[36:37], 0
	v_mov_b64_e32 v[38:39], 0
	v_mov_b64_e32 v[40:41], 0
	v_mov_b64_e32 v[42:43], 0
	v_mov_b64_e32 v[44:45], 0
	v_mov_b64_e32 v[46:47], 0
	v_mov_b64_e32 v[48:49], 0
	v_mov_b64_e32 v[82:83], 0
	v_mov_b64_e32 v[84:85], 0
	v_mov_b64_e32 v[86:87], 0
	v_mov_b64_e32 v[88:89], 0
	v_mov_b64_e32 v[90:91], 0
	v_mov_b64_e32 v[92:93], 0
	v_mov_b64_e32 v[94:95], 0
	v_mov_b64_e32 v[96:97], 0
	v_mov_b64_e32 v[98:99], 0
	v_mov_b64_e32 v[100:101], 0
	v_mov_b64_e32 v[102:103], 0
	v_mov_b64_e32 v[104:105], 0
	v_mov_b64_e32 v[106:107], 0
	v_mov_b64_e32 v[108:109], 0
	v_mov_b64_e32 v[110:111], 0
	v_mov_b64_e32 v[112:113], 0
	v_mov_b64_e32 v[114:115], 0
	v_mov_b64_e32 v[116:117], 0
	v_mov_b64_e32 v[118:119], 0
	v_mov_b64_e32 v[120:121], 0
	v_mov_b64_e32 v[122:123], 0
	v_mov_b64_e32 v[124:125], 0
	v_mov_b64_e32 v[126:127], 0
	v_mov_b64_e32 v[128:129], 0
	v_mov_b64_e32 v[130:131], 0
	v_mov_b64_e32 v[132:133], 0
	v_mov_b64_e32 v[134:135], 0
	v_mov_b64_e32 v[136:137], 0
	v_mov_b64_e32 v[138:139], 0
	v_mov_b64_e32 v[140:141], 0
	v_mov_b64_e32 v[142:143], 0
	v_mov_b64_e32 v[144:145], 0
	v_mov_b64_e32 v[146:147], 0
	v_mov_b64_e32 v[148:149], 0
	v_mov_b64_e32 v[150:151], 0
	v_mov_b64_e32 v[152:153], 0
	v_mov_b64_e32 v[154:155], 0
	v_mov_b64_e32 v[156:157], 0
	v_mov_b64_e32 v[158:159], 0
	v_mov_b64_e32 v[160:161], 0

; template <class Epi, class Sched>
; __device__ __forceinline__ void gemm_phase(LAS unsigned char* lds, const Gemm g, const Sched& S, const Epi& E, int wave_id) {
;     ...
;         const bool has_next = S.next(ui + 1, nxt);
;         const char* nA = has_next ? (const char*)g.A + nxt.a_off : cA; const char* nB = has_next ? (const char*)g.Bt + nxt.b_off : cB;
;         for (int t = 0; t < nt; t += 2) {
;             const bool last = (t == nt - 2);
;             const char* a1 = cA + (size_t)(t + 1) * kstep;
;             const char* a2 = last ? nA : cA + (size_t)(t + 2) * kstep; const char* b2 = last ? nB : cB + (size_t)(t + 2) * kstep;
;             const char* a3 = a2 + kstep; const char* b3 = b2 + kstep;
;     ...
;         for (int a = 0; a < 2; ++a)
; #pragma unroll
;             for (int b = 0; b < 2; ++b)
; #pragma unroll
;                 for (int m = 0; m < 4; ++m)
; #pragma unroll
;                     for (int n = 0; n < 2; ++n) acc[a][b][m][n] = (f32x4){0.f, 0.f, 0.f, 0.f};
.LBB0_474:
	s_add_u32 s52, s78, s48
	s_addc_u32 s53, s79, s49
	s_and_b64 s[8:9], s[44:45], exec
	v_readlane_b32 s8, v252, 59
	s_cselect_b32 s12, s53, s3
	s_cselect_b32 s13, s52, s2
	v_readlane_b32 s9, v252, 60
	s_add_u32 s54, s8, s50
	s_addc_u32 s55, s9, s51
	s_and_b64 s[8:9], s[44:45], exec
	s_cselect_b32 s18, s55, s7
	s_cselect_b32 s19, s54, s6
	s_add_u32 s21, s2, 0x100
	s_addc_u32 s22, s3, 0
	s_add_u32 s24, s6, 0x100
	s_addc_u32 s25, s7, 0
	s_add_u32 s26, s2, 0x80080
	v_mov_b32_e32 v2, 0
	s_addc_u32 s27, s3, 0
	s_mov_b32 s33, -2
	v_mov_b32_e32 v3, v2
	s_waitcnt lgkmcnt(1)
	v_mov_b32_e32 v4, v2
	s_waitcnt lgkmcnt(0)
	v_mov_b32_e32 v5, 0
	v_mov_b64_e32 v[6:7], 0
	v_mov_b64_e32 v[8:9], 0
	v_mov_b64_e32 v[10:11], 0
	v_mov_b64_e32 v[12:13], 0
	v_mov_b64_e32 v[14:15], 0
	v_mov_b64_e32 v[16:17], 0
	v_mov_b64_e32 v[18:19], 0
	v_mov_b64_e32 v[20:21], 0
	v_mov_b64_e32 v[22:23], 0
	v_mov_b64_e32 v[24:25], 0
	v_mov_b64_e32 v[26:27], 0
	v_mov_b64_e32 v[28:29], 0
	v_mov_b64_e32 v[30:31], 0
	v_mov_b64_e32 v[32:33], 0
	v_mov_b64_e32 v[34:35], 0
	v_mov_b64_e32 v[36:37], 0
	v_mov_b64_e32 v[38:39], 0
	v_mov_b64_e32 v[40:41], 0
	v_mov_b64_e32 v[42:43], 0
	v_mov_b64_e32 v[44:45], 0
	v_mov_b64_e32 v[46:47], 0
	v_mov_b64_e32 v[48:49], 0
	v_mov_b64_e32 v[50:51], 0
	v_mov_b64_e32 v[52:53], 0
	v_mov_b64_e32 v[54:55], 0
	v_mov_b64_e32 v[56:57], 0
	v_mov_b64_e32 v[58:59], 0
	v_mov_b64_e32 v[60:61], 0
	v_mov_b64_e32 v[62:63], 0
	v_mov_b64_e32 v[64:65], 0
	v_mov_b64_e32 v[66:67], 0
	v_mov_b64_e32 v[68:69], 0
	v_mov_b64_e32 v[70:71], 0
	v_mov_b64_e32 v[72:73], 0
	v_mov_b64_e32 v[74:75], 0
	v_mov_b64_e32 v[76:77], 0
	v_mov_b64_e32 v[78:79], 0
	v_mov_b64_e32 v[80:81], 0
	v_mov_b64_e32 v[82:83], 0
	v_mov_b64_e32 v[84:85], 0
	v_mov_b64_e32 v[86:87], 0
	v_mov_b64_e32 v[88:89], 0
	v_mov_b64_e32 v[90:91], 0
	v_mov_b64_e32 v[92:93], 0
	v_mov_b64_e32 v[94:95], 0
	v_mov_b64_e32 v[96:97], 0
	v_mov_b64_e32 v[98:99], 0
	v_mov_b64_e32 v[100:101], 0
	v_mov_b64_e32 v[102:103], 0
	v_mov_b64_e32 v[104:105], 0
	v_mov_b64_e32 v[106:107], 0
	v_mov_b64_e32 v[108:109], 0
	v_mov_b64_e32 v[110:111], 0
	v_mov_b64_e32 v[112:113], 0
	v_mov_b64_e32 v[114:115], 0
	v_mov_b64_e32 v[116:117], 0
	v_mov_b64_e32 v[118:119], 0
	v_mov_b64_e32 v[120:121], 0
	v_mov_b64_e32 v[122:123], 0
	v_mov_b64_e32 v[124:125], 0
	v_mov_b64_e32 v[126:127], 0
	v_mov_b64_e32 v[128:129], 0

; template <class Epi, class Sched>
; __device__ __forceinline__ void gemm_phase(LAS unsigned char* lds, const Gemm g, const Sched& S, const Epi& E, int wave_id) {
;     ...
;         const bool has_next = S.next(ui + 1, nxt);
;         const char* nA = has_next ? (const char*)g.A + nxt.a_off : cA; const char* nB = has_next ? (const char*)g.Bt + nxt.b_off : cB;
;         for (int t = 0; t < nt; t += 2) {
;             const bool last = (t == nt - 2);
;             const char* a1 = cA + (size_t)(t + 1) * kstep;
;             const char* a2 = last ? nA : cA + (size_t)(t + 2) * kstep; const char* b2 = last ? nB : cB + (size_t)(t + 2) * kstep;
;             const char* a3 = a2 + kstep; const char* b3 = b2 + kstep;
;     ...
;         for (int a = 0; a < 2; ++a)
; #pragma unroll
;             for (int b = 0; b < 2; ++b)
; #pragma unroll
;                 for (int m = 0; m < 4; ++m)
; #pragma unroll
;                     for (int n = 0; n < 2; ++n) acc[a][b][m][n] = (f32x4){0.f, 0.f, 0.f, 0.f};
.LBB0_616:
	s_add_u32 s48, s72, s40
	s_addc_u32 s49, s73, s41
	s_and_b64 s[6:7], s[44:45], exec
	v_readlane_b32 s6, v252, 17
	s_cselect_b32 s12, s49, s27
	s_cselect_b32 s13, s48, s26
	v_readlane_b32 s7, v252, 18
	s_add_u32 s50, s6, s46
	s_addc_u32 s51, s7, s47
	s_and_b64 s[6:7], s[44:45], exec
	s_cselect_b32 s18, s51, s3
	s_cselect_b32 s19, s50, s2
	s_add_u32 s21, s2, 0x100
	v_mov_b32_e32 v2, 0
	s_addc_u32 s22, s3, 0
	s_mov_b32 s24, -2
	v_mov_b64_e32 v[2:3], 0
	v_mov_b64_e32 v[4:5], 0
	v_mov_b64_e32 v[6:7], 0
	v_mov_b64_e32 v[8:9], 0
	v_mov_b64_e32 v[10:11], 0
	v_mov_b64_e32 v[12:13], 0
	v_mov_b64_e32 v[14:15], 0
	v_mov_b64_e32 v[16:17], 0
	v_mov_b64_e32 v[18:19], 0
	v_mov_b64_e32 v[20:21], 0
	v_mov_b64_e32 v[22:23], 0
	v_mov_b64_e32 v[24:25], 0
	v_mov_b64_e32 v[26:27], 0
	v_mov_b64_e32 v[28:29], 0
	v_mov_b64_e32 v[30:31], 0
	v_mov_b64_e32 v[32:33], 0
	v_mov_b64_e32 v[34:35], 0
	v_mov_b64_e32 v[36:37], 0
	v_mov_b64_e32 v[38:39], 0
	v_mov_b64_e32 v[40:41], 0
	v_mov_b64_e32 v[42:43], 0
	v_mov_b64_e32 v[44:45], 0
	v_mov_b64_e32 v[46:47], 0
	v_mov_b64_e32 v[48:49], 0
	v_mov_b64_e32 v[82:83], 0
	v_mov_b64_e32 v[84:85], 0
	v_mov_b64_e32 v[86:87], 0
	v_mov_b64_e32 v[88:89], 0
	v_mov_b64_e32 v[90:91], 0
	v_mov_b64_e32 v[92:93], 0
	v_mov_b64_e32 v[94:95], 0
	v_mov_b64_e32 v[96:97], 0
	v_mov_b64_e32 v[98:99], 0
	v_mov_b64_e32 v[100:101], 0
	v_mov_b64_e32 v[102:103], 0
	v_mov_b64_e32 v[104:105], 0
	v_mov_b64_e32 v[106:107], 0
	v_mov_b64_e32 v[108:109], 0
	v_mov_b64_e32 v[110:111], 0
	v_mov_b64_e32 v[112:113], 0
	v_mov_b64_e32 v[114:115], 0
	v_mov_b64_e32 v[116:117], 0
	v_mov_b64_e32 v[118:119], 0
	v_mov_b64_e32 v[120:121], 0
	v_mov_b64_e32 v[122:123], 0
	v_mov_b64_e32 v[124:125], 0
	v_mov_b64_e32 v[126:127], 0
	v_mov_b64_e32 v[128:129], 0
	v_mov_b64_e32 v[130:131], 0
	v_mov_b64_e32 v[132:133], 0
	v_mov_b64_e32 v[134:135], 0
	v_mov_b64_e32 v[136:137], 0
	v_mov_b64_e32 v[138:139], 0
	v_mov_b64_e32 v[140:141], 0
	v_mov_b64_e32 v[142:143], 0
	v_mov_b64_e32 v[144:145], 0
	v_mov_b64_e32 v[146:147], 0
	v_mov_b64_e32 v[148:149], 0
	v_mov_b64_e32 v[150:151], 0
	v_mov_b64_e32 v[152:153], 0
	v_mov_b64_e32 v[154:155], 0
	v_mov_b64_e32 v[156:157], 0
	v_mov_b64_e32 v[158:159], 0
	v_mov_b64_e32 v[160:161], 0

; template <class Epi, class Sched>
; __device__ __forceinline__ void gemm_phase(LAS unsigned char* lds, const Gemm g, const Sched& S, const Epi& E, int wave_id) {
;     ...
;         const bool has_next = S.next(ui + 1, nxt);
;         const char* nA = has_next ? (const char*)g.A + nxt.a_off : cA; const char* nB = has_next ? (const char*)g.Bt + nxt.b_off : cB;
;         for (int t = 0; t < nt; t += 2) {
;             const bool last = (t == nt - 2);
;             const char* a1 = cA + (size_t)(t + 1) * kstep;
;             const char* a2 = last ? nA : cA + (size_t)(t + 2) * kstep; const char* b2 = last ? nB : cB + (size_t)(t + 2) * kstep;
;             const char* a3 = a2 + kstep; const char* b3 = b2 + kstep;
;     ...
;         for (int a = 0; a < 2; ++a)
; #pragma unroll
;             for (int b = 0; b < 2; ++b)
; #pragma unroll
;                 for (int m = 0; m < 4; ++m)
; #pragma unroll
;                     for (int n = 0; n < 2; ++n) acc[a][b][m][n] = (f32x4){0.f, 0.f, 0.f, 0.f};
.LBB0_684:
	s_add_u32 s54, s74, s48
	s_addc_u32 s55, s75, s49
	s_and_b64 s[6:7], s[44:45], exec
	s_cselect_b32 s12, s55, s27
	s_cselect_b32 s13, s54, s26
	s_add_u32 s56, s17, s52
	s_addc_u32 s57, s16, s53
	s_and_b64 s[6:7], s[44:45], exec
	s_cselect_b32 s18, s57, s3
	s_cselect_b32 s19, s56, s2
	s_add_u32 s21, s2, 0x100
	v_mov_b32_e32 v2, 0
	s_addc_u32 s22, s3, 0
	s_mov_b32 s24, -2
	s_waitcnt lgkmcnt(0)
	v_mov_b64_e32 v[2:3], 0
	v_mov_b64_e32 v[4:5], 0
	v_mov_b64_e32 v[6:7], 0
	v_mov_b64_e32 v[8:9], 0
	v_mov_b64_e32 v[10:11], 0
	v_mov_b64_e32 v[12:13], 0
	v_mov_b64_e32 v[14:15], 0
	v_mov_b64_e32 v[16:17], 0
	v_mov_b64_e32 v[18:19], 0
	v_mov_b64_e32 v[20:21], 0
	v_mov_b64_e32 v[22:23], 0
	v_mov_b64_e32 v[24:25], 0
	v_mov_b64_e32 v[26:27], 0
	v_mov_b64_e32 v[28:29], 0
	v_mov_b64_e32 v[30:31], 0
	v_mov_b64_e32 v[32:33], 0
	v_mov_b64_e32 v[34:35], 0
	v_mov_b64_e32 v[36:37], 0
	v_mov_b64_e32 v[38:39], 0
	v_mov_b64_e32 v[40:41], 0
	v_mov_b64_e32 v[42:43], 0
	v_mov_b64_e32 v[44:45], 0
	v_mov_b64_e32 v[46:47], 0
	v_mov_b64_e32 v[48:49], 0
	v_mov_b64_e32 v[50:51], 0
	v_mov_b64_e32 v[52:53], 0
	v_mov_b64_e32 v[54:55], 0
	v_mov_b64_e32 v[56:57], 0
	v_mov_b64_e32 v[58:59], 0
	v_mov_b64_e32 v[60:61], 0
	v_mov_b64_e32 v[62:63], 0
	v_mov_b64_e32 v[64:65], 0
	v_mov_b64_e32 v[66:67], 0
	v_mov_b64_e32 v[68:69], 0
	v_mov_b64_e32 v[70:71], 0
	v_mov_b64_e32 v[72:73], 0
	v_mov_b64_e32 v[74:75], 0
	v_mov_b64_e32 v[76:77], 0
	v_mov_b64_e32 v[78:79], 0
	v_mov_b64_e32 v[80:81], 0
	v_mov_b64_e32 v[82:83], 0
	v_mov_b64_e32 v[84:85], 0
	v_mov_b64_e32 v[86:87], 0
	v_mov_b64_e32 v[88:89], 0
	v_mov_b64_e32 v[90:91], 0
	v_mov_b64_e32 v[92:93], 0
	v_mov_b64_e32 v[94:95], 0
	v_mov_b64_e32 v[96:97], 0
	v_mov_b64_e32 v[98:99], 0
	v_mov_b64_e32 v[100:101], 0
	v_mov_b64_e32 v[102:103], 0
	v_mov_b64_e32 v[104:105], 0
	v_mov_b64_e32 v[106:107], 0
	v_mov_b64_e32 v[108:109], 0
	v_mov_b64_e32 v[110:111], 0
	v_mov_b64_e32 v[112:113], 0
	v_mov_b64_e32 v[114:115], 0
	v_mov_b64_e32 v[116:117], 0
	v_mov_b64_e32 v[118:119], 0
	v_mov_b64_e32 v[120:121], 0
	v_mov_b64_e32 v[122:123], 0
	v_mov_b64_e32 v[124:125], 0
	v_mov_b64_e32 v[126:127], 0
	v_mov_b64_e32 v[128:129], 0

; template <class Epi, class Sched>
; __device__ __forceinline__ void gemm_phase(LAS unsigned char* lds, const Gemm g, const Sched& S, const Epi& E, int wave_id) {
;     ...
;         const bool has_next = S.next(ui + 1, nxt);
;         const char* nA = has_next ? (const char*)g.A + nxt.a_off : cA; const char* nB = has_next ? (const char*)g.Bt + nxt.b_off : cB;
;         for (int t = 0; t < nt; t += 2) {
;             const bool last = (t == nt - 2);
;             const char* a1 = cA + (size_t)(t + 1) * kstep;
;             const char* a2 = last ? nA : cA + (size_t)(t + 2) * kstep; const char* b2 = last ? nB : cB + (size_t)(t + 2) * kstep;
;             const char* a3 = a2 + kstep; const char* b3 = b2 + kstep;
;     ...
;         for (int a = 0; a < 2; ++a)
; #pragma unroll
;             for (int b = 0; b < 2; ++b)
; #pragma unroll
;                 for (int m = 0; m < 4; ++m)
; #pragma unroll
;                     for (int n = 0; n < 2; ++n) acc[a][b][m][n] = (f32x4){0.f, 0.f, 0.f, 0.f};
.LBB0_838:
	s_add_u32 s48, s78, s44
	s_addc_u32 s49, s79, s45
	s_and_b64 s[8:9], s[40:41], exec
	v_readlane_b32 s8, v253, 11
	s_cselect_b32 s12, s49, s3
	s_cselect_b32 s13, s48, s2
	v_readlane_b32 s9, v253, 12
	s_add_u32 s50, s8, s46
	s_addc_u32 s51, s9, s47
	s_and_b64 s[8:9], s[40:41], exec
	s_cselect_b32 s18, s51, s7
	s_cselect_b32 s19, s50, s6
	s_add_u32 s21, s2, 0x100
	s_addc_u32 s22, s3, 0
	s_add_u32 s24, s6, 0x100
	s_addc_u32 s25, s7, 0
	s_add_u32 s26, s2, 0x80080
	v_mov_b32_e32 v2, 0
	s_addc_u32 s27, s3, 0
	s_mov_b32 s33, -2
	v_mov_b32_e32 v3, v2
	s_waitcnt lgkmcnt(1)
	v_mov_b32_e32 v4, v2
	s_waitcnt lgkmcnt(0)
	v_mov_b32_e32 v5, 0
	v_mov_b64_e32 v[6:7], 0
	v_mov_b64_e32 v[8:9], 0
	v_mov_b64_e32 v[10:11], 0
	v_mov_b64_e32 v[12:13], 0
	v_mov_b64_e32 v[14:15], 0
	v_mov_b64_e32 v[16:17], 0
	v_mov_b64_e32 v[18:19], 0
	v_mov_b64_e32 v[20:21], 0
	v_mov_b64_e32 v[22:23], 0
	v_mov_b64_e32 v[24:25], 0
	v_mov_b64_e32 v[26:27], 0
	v_mov_b64_e32 v[28:29], 0
	v_mov_b64_e32 v[30:31], 0
	v_mov_b64_e32 v[32:33], 0
	v_mov_b64_e32 v[34:35], 0
	v_mov_b64_e32 v[36:37], 0
	v_mov_b64_e32 v[38:39], 0
	v_mov_b64_e32 v[40:41], 0
	v_mov_b64_e32 v[42:43], 0
	v_mov_b64_e32 v[44:45], 0
	v_mov_b64_e32 v[46:47], 0
	v_mov_b64_e32 v[48:49], 0
	v_mov_b64_e32 v[50:51], 0
	v_mov_b64_e32 v[52:53], 0
	v_mov_b64_e32 v[54:55], 0
	v_mov_b64_e32 v[56:57], 0
	v_mov_b64_e32 v[58:59], 0
	v_mov_b64_e32 v[60:61], 0
	v_mov_b64_e32 v[62:63], 0
	v_mov_b64_e32 v[64:65], 0
	v_mov_b64_e32 v[66:67], 0
	v_mov_b64_e32 v[68:69], 0
	v_mov_b64_e32 v[70:71], 0
	v_mov_b64_e32 v[72:73], 0
	v_mov_b64_e32 v[74:75], 0
	v_mov_b64_e32 v[76:77], 0
	v_mov_b64_e32 v[78:79], 0
	v_mov_b64_e32 v[80:81], 0
	v_mov_b64_e32 v[82:83], 0
	v_mov_b64_e32 v[84:85], 0
	v_mov_b64_e32 v[86:87], 0
	v_mov_b64_e32 v[88:89], 0
	v_mov_b64_e32 v[90:91], 0
	v_mov_b64_e32 v[92:93], 0
	v_mov_b64_e32 v[94:95], 0
	v_mov_b64_e32 v[96:97], 0
	v_mov_b64_e32 v[98:99], 0
	v_mov_b64_e32 v[100:101], 0
	v_mov_b64_e32 v[102:103], 0
	v_mov_b64_e32 v[104:105], 0
	v_mov_b64_e32 v[106:107], 0
	v_mov_b64_e32 v[108:109], 0
	v_mov_b64_e32 v[110:111], 0
	v_mov_b64_e32 v[112:113], 0
	v_mov_b64_e32 v[114:115], 0
	v_mov_b64_e32 v[116:117], 0
	v_mov_b64_e32 v[118:119], 0
	v_mov_b64_e32 v[120:121], 0
	v_mov_b64_e32 v[122:123], 0
	v_mov_b64_e32 v[124:125], 0
	v_mov_b64_e32 v[126:127], 0
	v_mov_b64_e32 v[128:129], 0

; template <class Epi, class Sched>
; __device__ __forceinline__ void gemm_phase(LAS unsigned char* lds, const Gemm g, const Sched& S, const Epi& E, int wave_id) {
;     ...
;         const bool has_next = S.next(ui + 1, nxt);
;         const char* nA = has_next ? (const char*)g.A + nxt.a_off : cA; const char* nB = has_next ? (const char*)g.Bt + nxt.b_off : cB;
;         for (int t = 0; t < nt; t += 2) {
;             const bool last = (t == nt - 2);
;             const char* a1 = cA + (size_t)(t + 1) * kstep;
;             const char* a2 = last ? nA : cA + (size_t)(t + 2) * kstep; const char* b2 = last ? nB : cB + (size_t)(t + 2) * kstep;
;             const char* a3 = a2 + kstep; const char* b3 = b2 + kstep;
;     ...
;         for (int a = 0; a < 2; ++a)
; #pragma unroll
;             for (int b = 0; b < 2; ++b)
; #pragma unroll
;                 for (int m = 0; m < 4; ++m)
; #pragma unroll
;                     for (int n = 0; n < 2; ++n) acc[a][b][m][n] = (f32x4){0.f, 0.f, 0.f, 0.f};
.LBB0_976:
	v_readlane_b32 s6, v255, 0
	v_readlane_b32 s7, v255, 1
	s_add_u32 s60, s6, s56
	s_addc_u32 s61, s7, s57
	s_and_b64 s[6:7], s[46:47], exec
	v_readlane_b32 s6, v253, 21
	s_cselect_b32 s12, s61, s27
	s_cselect_b32 s13, s60, s26
	v_readlane_b32 s7, v253, 22
	s_add_u32 s62, s6, s58
	s_addc_u32 s63, s7, s59
	s_and_b64 s[6:7], s[46:47], exec
	s_cselect_b32 s18, s63, s3
	s_cselect_b32 s19, s62, s2
	s_add_u32 s21, s2, 0x100
	v_mov_b32_e32 v26, 0
	s_addc_u32 s22, s3, 0
	s_mov_b32 s24, -2
	v_mov_b64_e32 v[2:3], 0
	v_mov_b64_e32 v[4:5], 0
	v_mov_b64_e32 v[6:7], 0
	v_mov_b64_e32 v[8:9], 0
	v_mov_b64_e32 v[10:11], 0
	v_mov_b64_e32 v[12:13], 0
	v_mov_b64_e32 v[14:15], 0
	v_mov_b64_e32 v[16:17], 0
	v_mov_b64_e32 v[18:19], 0
	v_mov_b64_e32 v[20:21], 0
	v_mov_b64_e32 v[22:23], 0
	v_mov_b64_e32 v[24:25], 0
	v_mov_b64_e32 v[26:27], 0
	v_mov_b64_e32 v[28:29], 0
	v_mov_b64_e32 v[30:31], 0
	v_mov_b64_e32 v[32:33], 0
	v_mov_b64_e32 v[34:35], 0
	v_mov_b64_e32 v[36:37], 0
	v_mov_b64_e32 v[38:39], 0
	v_mov_b64_e32 v[40:41], 0
	v_mov_b64_e32 v[42:43], 0
	v_mov_b64_e32 v[44:45], 0
	v_mov_b64_e32 v[46:47], 0
	v_mov_b64_e32 v[48:49], 0
	v_mov_b64_e32 v[50:51], 0
	v_mov_b64_e32 v[52:53], 0
	v_mov_b64_e32 v[54:55], 0
	v_mov_b64_e32 v[56:57], 0
	v_mov_b64_e32 v[58:59], 0
	v_mov_b64_e32 v[60:61], 0
	v_mov_b64_e32 v[62:63], 0
	v_mov_b64_e32 v[64:65], 0
	v_mov_b64_e32 v[66:67], 0
	v_mov_b64_e32 v[68:69], 0
	v_mov_b64_e32 v[70:71], 0
	v_mov_b64_e32 v[72:73], 0
	v_mov_b64_e32 v[74:75], 0
	v_mov_b64_e32 v[76:77], 0
	v_mov_b64_e32 v[78:79], 0
	v_mov_b64_e32 v[80:81], 0
	v_mov_b64_e32 v[82:83], 0
	v_mov_b64_e32 v[84:85], 0
	v_mov_b64_e32 v[86:87], 0
	v_mov_b64_e32 v[88:89], 0
	v_mov_b64_e32 v[90:91], 0
	v_mov_b64_e32 v[92:93], 0
	v_mov_b64_e32 v[94:95], 0
	v_mov_b64_e32 v[96:97], 0
	v_mov_b64_e32 v[98:99], 0
	v_mov_b64_e32 v[100:101], 0
	v_mov_b64_e32 v[102:103], 0
	v_mov_b64_e32 v[104:105], 0
	v_mov_b64_e32 v[106:107], 0
	v_mov_b64_e32 v[108:109], 0
	v_mov_b64_e32 v[110:111], 0
	v_mov_b64_e32 v[112:113], 0
	v_mov_b64_e32 v[114:115], 0
	v_mov_b64_e32 v[116:117], 0
	v_mov_b64_e32 v[118:119], 0
	v_mov_b64_e32 v[120:121], 0
	v_mov_b64_e32 v[122:123], 0
	v_mov_b64_e32 v[124:125], 0
	v_mov_b64_e32 v[126:127], 0
	v_mov_b64_e32 v[128:129], 0

; template <class Epi, class Sched>
; __device__ __forceinline__ void gemm_phase(LAS unsigned char* lds, const Gemm g, const Sched& S, const Epi& E, int wave_id) {
;     ...
;         const bool has_next = S.next(ui + 1, nxt);
;         const char* nA = has_next ? (const char*)g.A + nxt.a_off : cA; const char* nB = has_next ? (const char*)g.Bt + nxt.b_off : cB;
;         for (int t = 0; t < nt; t += 2) {
;             const bool last = (t == nt - 2);
;             const char* a1 = cA + (size_t)(t + 1) * kstep;
;             const char* a2 = last ? nA : cA + (size_t)(t + 2) * kstep; const char* b2 = last ? nB : cB + (size_t)(t + 2) * kstep;
;             const char* a3 = a2 + kstep; const char* b3 = b2 + kstep;
;     ...
;         for (int a = 0; a < 2; ++a)
; #pragma unroll
;             for (int b = 0; b < 2; ++b)
; #pragma unroll
;                 for (int m = 0; m < 4; ++m)
; #pragma unroll
;                     for (int n = 0; n < 2; ++n) acc[a][b][m][n] = (f32x4){0.f, 0.f, 0.f, 0.f};
.LBB0_1144:
	s_add_u32 s48, s74, s44
	s_addc_u32 s49, s75, s45
	s_and_b64 s[6:7], s[40:41], exec
	v_readlane_b32 s6, v252, 43
	s_cselect_b32 s12, s49, s27
	s_cselect_b32 s13, s48, s26
	v_readlane_b32 s7, v252, 44
	s_add_u32 s50, s6, s46
	s_addc_u32 s51, s7, s47
	s_and_b64 s[6:7], s[40:41], exec
	s_cselect_b32 s18, s51, s3
	s_cselect_b32 s19, s50, s2
	s_add_u32 s21, s2, 0x100
	v_mov_b32_e32 v2, 0
	s_addc_u32 s22, s3, 0
	s_mov_b32 s24, -2
	v_mov_b64_e32 v[2:3], 0
	v_mov_b64_e32 v[4:5], 0
	v_mov_b64_e32 v[6:7], 0
	v_mov_b64_e32 v[8:9], 0
	v_mov_b64_e32 v[10:11], 0
	v_mov_b64_e32 v[12:13], 0
	v_mov_b64_e32 v[14:15], 0
	v_mov_b64_e32 v[16:17], 0
	v_mov_b64_e32 v[18:19], 0
	v_mov_b64_e32 v[20:21], 0
	v_mov_b64_e32 v[22:23], 0
	v_mov_b64_e32 v[24:25], 0
	v_mov_b64_e32 v[26:27], 0
	v_mov_b64_e32 v[28:29], 0
	v_mov_b64_e32 v[30:31], 0
	v_mov_b64_e32 v[32:33], 0
	v_mov_b64_e32 v[34:35], 0
	v_mov_b64_e32 v[36:37], 0
	v_mov_b64_e32 v[38:39], 0
	v_mov_b64_e32 v[40:41], 0
	v_mov_b64_e32 v[42:43], 0
	v_mov_b64_e32 v[44:45], 0
	v_mov_b64_e32 v[46:47], 0
	v_mov_b64_e32 v[48:49], 0
	v_mov_b64_e32 v[50:51], 0
	v_mov_b64_e32 v[52:53], 0
	v_mov_b64_e32 v[54:55], 0
	v_mov_b64_e32 v[56:57], 0
	v_mov_b64_e32 v[58:59], 0
	v_mov_b64_e32 v[60:61], 0
	v_mov_b64_e32 v[62:63], 0
	v_mov_b64_e32 v[64:65], 0
	v_mov_b64_e32 v[66:67], 0
	v_mov_b64_e32 v[68:69], 0
	v_mov_b64_e32 v[70:71], 0
	v_mov_b64_e32 v[72:73], 0
	v_mov_b64_e32 v[74:75], 0
	v_mov_b64_e32 v[76:77], 0
	v_mov_b64_e32 v[78:79], 0
	v_mov_b64_e32 v[80:81], 0
	v_mov_b64_e32 v[82:83], 0
	v_mov_b64_e32 v[84:85], 0
	v_mov_b64_e32 v[86:87], 0
	v_mov_b64_e32 v[88:89], 0
	v_mov_b64_e32 v[90:91], 0
	v_mov_b64_e32 v[92:93], 0
	v_mov_b64_e32 v[94:95], 0
	v_mov_b64_e32 v[96:97], 0
	v_mov_b64_e32 v[98:99], 0
	v_mov_b64_e32 v[100:101], 0
	v_mov_b64_e32 v[102:103], 0
	v_mov_b64_e32 v[104:105], 0
	v_mov_b64_e32 v[106:107], 0
	v_mov_b64_e32 v[108:109], 0
	v_mov_b64_e32 v[110:111], 0
	v_mov_b64_e32 v[112:113], 0
	v_mov_b64_e32 v[114:115], 0
	v_mov_b64_e32 v[116:117], 0
	v_mov_b64_e32 v[118:119], 0
	v_mov_b64_e32 v[120:121], 0
	v_mov_b64_e32 v[122:123], 0
	v_mov_b64_e32 v[124:125], 0
	v_mov_b64_e32 v[126:127], 0
	v_mov_b64_e32 v[128:129], 0

; template <class Epi, class Sched>
; __device__ __forceinline__ void gemm_phase(LAS unsigned char* lds, const Gemm g, const Sched& S, const Epi& E, int wave_id) {
;     ...
;         const bool has_next = S.next(ui + 1, nxt);
;         const char* nA = has_next ? (const char*)g.A + nxt.a_off : cA; const char* nB = has_next ? (const char*)g.Bt + nxt.b_off : cB;
;         for (int t = 0; t < nt; t += 2) {
;             const bool last = (t == nt - 2);
;             const char* a1 = cA + (size_t)(t + 1) * kstep;
;             const char* a2 = last ? nA : cA + (size_t)(t + 2) * kstep; const char* b2 = last ? nB : cB + (size_t)(t + 2) * kstep;
;             const char* a3 = a2 + kstep; const char* b3 = b2 + kstep;
;     ...
;         for (int a = 0; a < 2; ++a)
; #pragma unroll
;             for (int b = 0; b < 2; ++b)
; #pragma unroll
;                 for (int m = 0; m < 4; ++m)
; #pragma unroll
;                     for (int n = 0; n < 2; ++n) acc[a][b][m][n] = (f32x4){0.f, 0.f, 0.f, 0.f};
.LBB0_1166:
	s_add_u32 s46, s74, s42
	s_addc_u32 s47, s75, s43
	s_and_b64 s[8:9], s[40:41], exec
	v_readlane_b32 s8, v252, 43
	s_cselect_b32 s12, s47, s3
	s_cselect_b32 s13, s46, s2
	v_readlane_b32 s9, v252, 44
	s_add_u32 s48, s8, s44
	s_addc_u32 s49, s9, s45
	s_and_b64 s[8:9], s[40:41], exec
	s_cselect_b32 s18, s49, s7
	s_cselect_b32 s19, s48, s6
	s_add_u32 s21, s2, 0x100
	s_addc_u32 s22, s3, 0
	s_add_u32 s24, s6, 0x100
	s_addc_u32 s25, s7, 0
	s_add_u32 s26, s2, 0x160080
	v_mov_b32_e32 v2, 0
	s_addc_u32 s27, s3, 0
	s_mov_b32 s33, -2
	v_mov_b32_e32 v3, v2
	s_waitcnt lgkmcnt(1)
	v_mov_b32_e32 v4, v2
	s_waitcnt lgkmcnt(0)
	v_mov_b32_e32 v5, 0
	v_mov_b64_e32 v[6:7], 0
	v_mov_b64_e32 v[8:9], 0
	v_mov_b64_e32 v[10:11], 0
	v_mov_b64_e32 v[12:13], 0
	v_mov_b64_e32 v[14:15], 0
	v_mov_b64_e32 v[16:17], 0
	v_mov_b64_e32 v[18:19], 0
	v_mov_b64_e32 v[20:21], 0
	v_mov_b64_e32 v[22:23], 0
	v_mov_b64_e32 v[24:25], 0
	v_mov_b64_e32 v[26:27], 0
	v_mov_b64_e32 v[28:29], 0
	v_mov_b64_e32 v[30:31], 0
	v_mov_b64_e32 v[32:33], 0
	v_mov_b64_e32 v[34:35], 0
	v_mov_b64_e32 v[36:37], 0
	v_mov_b64_e32 v[38:39], 0
	v_mov_b64_e32 v[40:41], 0
	v_mov_b64_e32 v[42:43], 0
	v_mov_b64_e32 v[44:45], 0
	v_mov_b64_e32 v[46:47], 0
	v_mov_b64_e32 v[48:49], 0
	v_mov_b64_e32 v[50:51], 0
	v_mov_b64_e32 v[52:53], 0
	v_mov_b64_e32 v[54:55], 0
	v_mov_b64_e32 v[56:57], 0
	v_mov_b64_e32 v[58:59], 0
	v_mov_b64_e32 v[60:61], 0
	v_mov_b64_e32 v[62:63], 0
	v_mov_b64_e32 v[64:65], 0
	v_mov_b64_e32 v[66:67], 0
	v_mov_b64_e32 v[68:69], 0
	v_mov_b64_e32 v[70:71], 0
	v_mov_b64_e32 v[72:73], 0
	v_mov_b64_e32 v[74:75], 0
	v_mov_b64_e32 v[76:77], 0
	v_mov_b64_e32 v[78:79], 0
	v_mov_b64_e32 v[80:81], 0
	v_mov_b64_e32 v[82:83], 0
	v_mov_b64_e32 v[84:85], 0
	v_mov_b64_e32 v[86:87], 0
	v_mov_b64_e32 v[88:89], 0
	v_mov_b64_e32 v[90:91], 0
	v_mov_b64_e32 v[92:93], 0
	v_mov_b64_e32 v[94:95], 0
	v_mov_b64_e32 v[96:97], 0
	v_mov_b64_e32 v[98:99], 0
	v_mov_b64_e32 v[100:101], 0
	v_mov_b64_e32 v[102:103], 0
	v_mov_b64_e32 v[104:105], 0
	v_mov_b64_e32 v[106:107], 0
	v_mov_b64_e32 v[108:109], 0
	v_mov_b64_e32 v[110:111], 0
	v_mov_b64_e32 v[112:113], 0
	v_mov_b64_e32 v[114:115], 0
	v_mov_b64_e32 v[116:117], 0
	v_mov_b64_e32 v[118:119], 0
	v_mov_b64_e32 v[120:121], 0
	v_mov_b64_e32 v[122:123], 0
	v_mov_b64_e32 v[124:125], 0
	v_mov_b64_e32 v[126:127], 0
	v_mov_b64_e32 v[128:129], 0
